# baseline (speedup 1.0000x reference)
; #define MFMA_FENCE() do { __builtin_amdgcn_sched_barrier(0); asm volatile("s_nop 15\n\ts_nop 15" ::: "memory"); __builtin_amdgcn_sched_barrier(0); } while (0)
; DEVI f32x16 mfma32(bf16x8 a, bf16x8 b, f32x16 c) { return __builtin_amdgcn_mfma_f32_32x32x16_bf16(a, b, c, 0, 0, 0); }
; template <bool SBK>
; __device__ __forceinline__ void attn_item(KP p, int layer, int b, int hh, int qt, char* smem, int tix) {
;     ...
;     if (kt * 64 <= qmax_w && !sb_done) {
;       f32x16 s[2];
;       __builtin_amdgcn_s_setprio(1);
; #pragma unroll
;       for (int kb2 = 0; kb2 < 2; ++kb2) {
; #pragma unroll
;         for (int r = 0; r < 16; ++r) s[kb2][r] = 0.f;
; #pragma unroll
;         for (int ks = 0; ks < 4; ++ks) {
;           bf16x8 a = *(const bf16x8*)(kb + (kb2 * 32 + l32) * KST + c * 64 + ks * 16 + hf * 8);
;           s[kb2] = mfma32(a, qf[ks], s[kb2]);
;         }
;       }
;       __builtin_amdgcn_s_setprio(0);
;       bf16x8 pf[2][2];
;       MFMA_FENCE();
;       if (!SBK) {
;         const bool need_mask = (kt * 64 + 63 > qmin_w) || (kt == 1);
;         float mx = -1e30f;
; #pragma unroll
;         for (int kb2 = 0; kb2 < 2; ++kb2)
; #pragma unroll
;           for (int r = 0; r < 16; ++r) {
;             float t = s[kb2][r] * sc2;
;             if (need_mask) {
;               int kp = kt * 64 + kb2 * 32 + 8 * (r >> 2) + 4 * hf + (r & 3);
;               if (kp < PADF || kp > qpos) t = -1e30f;
;             }
;             s[kb2][r] = t;
;             mx = fmaxf(mx, t);
;           }
.LBB0_389:
	s_or_b64 exec, exec, s[6:7]
	s_sub_i32 s6, s14, 64
	v_cmp_le_i32_e32 vcc, s6, v141
	s_and_saveexec_b64 s[18:19], vcc
	s_cbranch_execz .LBB0_393
	s_bitcmp1_b32 s8, 0
	s_setprio 1
	s_cselect_b32 s7, 0x2200, 0
	s_lshl_b32 s15, s7, 1
	v_add3_u32 v161, v151, s15, v157
	ds_read_b128 v[194:197], v161
	ds_read_b128 v[210:213], v161 offset:8704
	ds_read_b128 v[198:201], v161 offset:32
	ds_read_b128 v[214:217], v161 offset:8736
	ds_read_b128 v[202:205], v161 offset:64
	ds_read_b128 v[218:221], v161 offset:8768
	ds_read_b128 v[206:209], v161 offset:96
	ds_read_b128 v[222:225], v161 offset:8800
	s_waitcnt lgkmcnt(7)
	v_mfma_f32_32x32x16_bf16 v[82:97], v[194:197], v[98:101], 0
	s_waitcnt lgkmcnt(6)
	v_mfma_f32_32x32x16_bf16 v[66:81], v[210:213], v[98:101], 0
	s_waitcnt lgkmcnt(5)
	v_mfma_f32_32x32x16_bf16 v[82:97], v[198:201], v[102:105], v[82:97]
	s_waitcnt lgkmcnt(4)
	v_mfma_f32_32x32x16_bf16 v[66:81], v[214:217], v[102:105], v[66:81]
	s_waitcnt lgkmcnt(3)
	v_mfma_f32_32x32x16_bf16 v[82:97], v[202:205], v[106:109], v[82:97]
	s_waitcnt lgkmcnt(2)
	v_mfma_f32_32x32x16_bf16 v[66:81], v[218:221], v[106:109], v[66:81]
	s_waitcnt lgkmcnt(1)
	v_mfma_f32_32x32x16_bf16 v[82:97], v[206:209], v[110:113], v[82:97]
	s_waitcnt lgkmcnt(0)
	v_mfma_f32_32x32x16_bf16 v[66:81], v[222:225], v[110:113], v[66:81]
	s_setprio 0
	v_add3_u32 v242, v152, s15, v159
	v_add_u32_e32 v243, 0x8800, v242
	ds_read2_b64 v[194:197], v243 offset1:2
	ds_read2_b64 v[198:201], v243 offset0:4 offset1:6
	ds_read2_b64 v[202:205], v243 offset0:8 offset1:10
	ds_read2_b64 v[206:209], v243 offset0:12 offset1:14
	v_add_u32_e32 v243, 0x9800, v242
	ds_read2_b64 v[210:213], v243 offset0:32 offset1:34
	ds_read2_b64 v[214:217], v243 offset0:36 offset1:38
	ds_read2_b64 v[218:221], v243 offset0:40 offset1:42
	ds_read2_b64 v[222:225], v243 offset0:44 offset1:46
	v_add_u32_e32 v243, 0xa800, v242
	ds_read2_b64 v[226:229], v243 offset0:64 offset1:66
	ds_read2_b64 v[230:233], v243 offset0:68 offset1:70
	ds_read2_b64 v[234:237], v243 offset0:72 offset1:74
	ds_read2_b64 v[238:241], v243 offset0:76 offset1:78
	s_nop 3
	s_add_i32 s7, s14, -1
	v_add_u32_e32 v161, s14, v134
	v_subrev_u32_e32 v162, 64, v161
	s_cmpk_lt_u32 s6, 0x70
	v_cmp_gt_i32_e32 vcc, s7, v148
	s_cbranch_vccz .Ldiff_fast
	s_cselect_b64 s[8:9], -1, 0
	v_cmp_gt_i32_e64 s[6:7], v162, v133
	s_or_b64 s[6:7], s[8:9], s[6:7]
	v_mul_f32_e32 v82, 0x3e38aa3b, v82
	s_and_b64 s[6:7], vcc, s[6:7]
	v_cndmask_b32_e64 v82, v82, v182, s[6:7]
	v_cmp_ge_i32_e64 s[6:7], v162, v133
	s_or_b64 s[6:7], s[8:9], s[6:7]
	v_mul_f32_e32 v83, 0x3e38aa3b, v83
	s_and_b64 s[6:7], vcc, s[6:7]
	v_subrev_u32_e32 v163, 62, v161
	v_cndmask_b32_e64 v83, v83, v182, s[6:7]
	v_cmp_gt_i32_e64 s[6:7], v163, v133
	s_or_b64 s[6:7], s[8:9], s[6:7]
	v_mul_f32_e32 v84, 0x3e38aa3b, v84
	s_and_b64 s[6:7], vcc, s[6:7]
	v_subrev_u32_e32 v163, 61, v161
	v_cndmask_b32_e64 v84, v84, v182, s[6:7]
	v_cmp_gt_i32_e64 s[6:7], v163, v133
	s_or_b64 s[6:7], s[8:9], s[6:7]
	v_mul_f32_e32 v85, 0x3e38aa3b, v85
	s_and_b64 s[6:7], vcc, s[6:7]
	v_subrev_u32_e32 v163, 56, v161
	v_cndmask_b32_e64 v85, v85, v182, s[6:7]
	v_cmp_gt_i32_e64 s[6:7], v163, v133
	s_or_b64 s[6:7], s[8:9], s[6:7]
	v_mul_f32_e32 v86, 0x3e38aa3b, v86
	s_and_b64 s[6:7], vcc, s[6:7]
	v_subrev_u32_e32 v163, 55, v161
	v_cndmask_b32_e64 v86, v86, v182, s[6:7]
	v_cmp_gt_i32_e64 s[6:7], v163, v133
	s_or_b64 s[6:7], s[8:9], s[6:7]
	v_mul_f32_e32 v87, 0x3e38aa3b, v87
	s_and_b64 s[6:7], vcc, s[6:7]
	v_subrev_u32_e32 v163, 54, v161
	v_cndmask_b32_e64 v87, v87, v182, s[6:7]
	v_cmp_gt_i32_e64 s[6:7], v163, v133
	s_or_b64 s[6:7], s[8:9], s[6:7]
	v_mul_f32_e32 v88, 0x3e38aa3b, v88
	s_and_b64 s[6:7], vcc, s[6:7]
	v_subrev_u32_e32 v163, 53, v161
	v_cndmask_b32_e64 v88, v88, v182, s[6:7]
	v_cmp_gt_i32_e64 s[6:7], v163, v133
	s_or_b64 s[6:7], s[8:9], s[6:7]
	v_mul_f32_e32 v89, 0x3e38aa3b, v89
	s_and_b64 s[6:7], vcc, s[6:7]
	v_subrev_u32_e32 v163, 48, v161
	v_cndmask_b32_e64 v89, v89, v182, s[6:7]
	v_cmp_gt_u32_e64 s[6:7], s53, v163
	v_cmp_gt_i32_e64 s[8:9], v163, v133
	s_or_b64 s[6:7], s[6:7], s[8:9]
	v_mul_f32_e32 v90, 0x3e38aa3b, v90
	s_and_b64 s[6:7], vcc, s[6:7]
	v_subrev_u32_e32 v163, 47, v161
	v_cndmask_b32_e64 v90, v90, v182, s[6:7]
	v_cmp_gt_u32_e64 s[6:7], s53, v163
	v_cmp_gt_i32_e64 s[8:9], v163, v133
	s_or_b64 s[6:7], s[6:7], s[8:9]
	v_mul_f32_e32 v91, 0x3e38aa3b, v91
	s_and_b64 s[6:7], vcc, s[6:7]
	v_subrev_u32_e32 v163, 46, v161
	v_cndmask_b32_e64 v91, v91, v182, s[6:7]
	v_cmp_gt_u32_e64 s[6:7], s53, v163
	v_cmp_gt_i32_e64 s[8:9], v163, v133
	s_or_b64 s[6:7], s[6:7], s[8:9]
	v_mul_f32_e32 v92, 0x3e38aa3b, v92
	s_and_b64 s[6:7], vcc, s[6:7]
	v_subrev_u32_e32 v163, 45, v161
	v_cndmask_b32_e64 v92, v92, v182, s[6:7]
	v_cmp_gt_u32_e64 s[6:7], s53, v163
	v_cmp_gt_i32_e64 s[8:9], v163, v133
	s_or_b64 s[6:7], s[6:7], s[8:9]
	v_mul_f32_e32 v93, 0x3e38aa3b, v93
	s_and_b64 s[6:7], vcc, s[6:7]
	v_subrev_u32_e32 v163, 40, v161
	v_cndmask_b32_e64 v93, v93, v182, s[6:7]
	v_cmp_gt_u32_e64 s[6:7], s53, v163
	v_cmp_gt_i32_e64 s[8:9], v163, v133
	s_or_b64 s[6:7], s[6:7], s[8:9]
	v_mul_f32_e32 v94, 0x3e38aa3b, v94
	s_and_b64 s[6:7], vcc, s[6:7]
	v_subrev_u32_e32 v163, 39, v161
	v_cndmask_b32_e64 v94, v94, v182, s[6:7]
; DEVI float max32x(float v) { float a, b; swap32(v, a, b); return fmaxf(a, b); }
; template <bool SBK>
; __device__ __forceinline__ void attn_item(KP p, int layer, int b, int hh, int qt, char* smem, int tix) {
;     ...
;         for (int kb2 = 0; kb2 < 2; ++kb2)
; #pragma unroll
;           for (int r = 0; r < 16; ++r) {
;             float t = s[kb2][r] * sc2;
;             if (need_mask) {
;               int kp = kt * 64 + kb2 * 32 + 8 * (r >> 2) + 4 * hf + (r & 3);
;               if (kp < PADF || kp > qpos) t = -1e30f;
;             }
;             s[kb2][r] = t;
;             mx = fmaxf(mx, t);
;           }
;         mx = max32x(mx);
	v_cmp_gt_u32_e64 s[6:7], s53, v163
	v_cmp_gt_i32_e64 s[8:9], v163, v133
	s_or_b64 s[6:7], s[6:7], s[8:9]
	v_mul_f32_e32 v95, 0x3e38aa3b, v95
	s_and_b64 s[6:7], vcc, s[6:7]
	v_subrev_u32_e32 v163, 38, v161
	v_cndmask_b32_e64 v95, v95, v182, s[6:7]
	v_cmp_gt_u32_e64 s[6:7], s53, v163
	v_cmp_gt_i32_e64 s[8:9], v163, v133
	s_or_b64 s[6:7], s[6:7], s[8:9]
	v_mul_f32_e32 v96, 0x3e38aa3b, v96
	s_and_b64 s[6:7], vcc, s[6:7]
	v_subrev_u32_e32 v163, 37, v161
	v_cndmask_b32_e64 v96, v96, v182, s[6:7]
	v_cmp_gt_u32_e64 s[6:7], s53, v163
	v_cmp_gt_i32_e64 s[8:9], v163, v133
	s_or_b64 s[6:7], s[6:7], s[8:9]
	v_mul_f32_e32 v97, 0x3e38aa3b, v97
	s_and_b64 s[6:7], vcc, s[6:7]
	v_subrev_u32_e32 v163, 32, v161
	v_cndmask_b32_e64 v97, v97, v182, s[6:7]
	v_cmp_gt_u32_e64 s[6:7], s53, v163
	v_cmp_gt_i32_e64 s[8:9], v163, v133
	s_or_b64 s[6:7], s[6:7], s[8:9]
	v_mul_f32_e32 v66, 0x3e38aa3b, v66
	s_and_b64 s[6:7], vcc, s[6:7]
	v_subrev_u32_e32 v163, 31, v161
	v_cndmask_b32_e64 v66, v66, v182, s[6:7]
	v_cmp_gt_u32_e64 s[6:7], s53, v163
	v_cmp_gt_i32_e64 s[8:9], v163, v133
	s_or_b64 s[6:7], s[6:7], s[8:9]
	v_mul_f32_e32 v67, 0x3e38aa3b, v67
	s_and_b64 s[6:7], vcc, s[6:7]
	v_subrev_u32_e32 v163, 30, v161
	v_cndmask_b32_e64 v67, v67, v182, s[6:7]
	v_cmp_gt_u32_e64 s[6:7], s53, v163
	v_cmp_gt_i32_e64 s[8:9], v163, v133
	s_or_b64 s[6:7], s[6:7], s[8:9]
	v_mul_f32_e32 v68, 0x3e38aa3b, v68
	s_and_b64 s[6:7], vcc, s[6:7]
	v_subrev_u32_e32 v163, 29, v161
	v_cndmask_b32_e64 v68, v68, v182, s[6:7]
	v_cmp_gt_u32_e64 s[6:7], s53, v163
	v_cmp_gt_i32_e64 s[8:9], v163, v133
	s_or_b64 s[6:7], s[6:7], s[8:9]
	v_mul_f32_e32 v69, 0x3e38aa3b, v69
	s_and_b64 s[6:7], vcc, s[6:7]
	v_subrev_u32_e32 v163, 24, v161
	v_cndmask_b32_e64 v69, v69, v182, s[6:7]
	v_cmp_gt_u32_e64 s[6:7], s53, v163
	v_cmp_gt_i32_e64 s[8:9], v163, v133
	s_or_b64 s[6:7], s[6:7], s[8:9]
	v_mul_f32_e32 v70, 0x3e38aa3b, v70
	s_and_b64 s[6:7], vcc, s[6:7]
	v_subrev_u32_e32 v163, 23, v161
	v_cndmask_b32_e64 v70, v70, v182, s[6:7]
	v_cmp_gt_u32_e64 s[6:7], s53, v163
	v_cmp_gt_i32_e64 s[8:9], v163, v133
	s_or_b64 s[6:7], s[6:7], s[8:9]
	v_mul_f32_e32 v71, 0x3e38aa3b, v71
	s_and_b64 s[6:7], vcc, s[6:7]
	v_subrev_u32_e32 v163, 22, v161
	v_cndmask_b32_e64 v71, v71, v182, s[6:7]
	v_cmp_gt_u32_e64 s[6:7], s53, v163
	v_cmp_gt_i32_e64 s[8:9], v163, v133
	s_or_b64 s[6:7], s[6:7], s[8:9]
	v_mul_f32_e32 v72, 0x3e38aa3b, v72
	s_and_b64 s[6:7], vcc, s[6:7]
	v_subrev_u32_e32 v163, 21, v161
	v_cndmask_b32_e64 v72, v72, v182, s[6:7]
	v_cmp_gt_u32_e64 s[6:7], s53, v163
	v_cmp_gt_i32_e64 s[8:9], v163, v133
	s_or_b64 s[6:7], s[6:7], s[8:9]
	v_mul_f32_e32 v73, 0x3e38aa3b, v73
	s_and_b64 s[6:7], vcc, s[6:7]
	v_add_u32_e32 v163, -16, v161
	v_cndmask_b32_e64 v73, v73, v182, s[6:7]
	v_cmp_gt_u32_e64 s[6:7], s53, v163
	v_cmp_gt_i32_e64 s[8:9], v163, v133
	s_or_b64 s[6:7], s[6:7], s[8:9]
	v_mul_f32_e32 v74, 0x3e38aa3b, v74
	s_and_b64 s[6:7], vcc, s[6:7]
	v_add_u32_e32 v163, -15, v161
	v_cndmask_b32_e64 v74, v74, v182, s[6:7]
	v_cmp_gt_u32_e64 s[6:7], s53, v163
	v_cmp_gt_i32_e64 s[8:9], v163, v133
	s_or_b64 s[6:7], s[6:7], s[8:9]
	v_mul_f32_e32 v75, 0x3e38aa3b, v75
	s_and_b64 s[6:7], vcc, s[6:7]
	v_add_u32_e32 v163, -14, v161
	v_cndmask_b32_e64 v75, v75, v182, s[6:7]
	v_cmp_gt_u32_e64 s[6:7], s53, v163
	v_cmp_gt_i32_e64 s[8:9], v163, v133
	s_or_b64 s[6:7], s[6:7], s[8:9]
	v_mul_f32_e32 v76, 0x3e38aa3b, v76
	s_and_b64 s[6:7], vcc, s[6:7]
	v_add_u32_e32 v163, -13, v161
	v_cndmask_b32_e64 v76, v76, v182, s[6:7]
	v_cmp_gt_u32_e64 s[6:7], s53, v163
	v_cmp_gt_i32_e64 s[8:9], v163, v133
	v_max3_f32 v162, v82, s23, v83
	s_or_b64 s[6:7], s[6:7], s[8:9]
	v_max3_f32 v162, v162, v84, v85
	v_mul_f32_e32 v77, 0x3e38aa3b, v77
	s_and_b64 s[6:7], vcc, s[6:7]
	v_add_u32_e32 v163, -8, v161
	v_max3_f32 v162, v162, v86, v87
	v_cndmask_b32_e64 v77, v77, v182, s[6:7]
	v_cmp_gt_u32_e64 s[6:7], s53, v163
	v_cmp_gt_i32_e64 s[8:9], v163, v133
	v_max3_f32 v162, v162, v88, v89
	s_or_b64 s[6:7], s[6:7], s[8:9]
	v_max3_f32 v162, v162, v90, v91
	v_mul_f32_e32 v78, 0x3e38aa3b, v78
	s_and_b64 s[6:7], vcc, s[6:7]
	v_add_u32_e32 v163, -7, v161
	v_max3_f32 v162, v162, v92, v93
	v_cndmask_b32_e64 v78, v78, v182, s[6:7]
	v_cmp_gt_u32_e64 s[6:7], s53, v163
	v_cmp_gt_i32_e64 s[8:9], v163, v133
	v_max3_f32 v162, v162, v94, v95
	s_or_b64 s[6:7], s[6:7], s[8:9]
	v_max3_f32 v162, v162, v96, v97
	v_mul_f32_e32 v79, 0x3e38aa3b, v79
	s_and_b64 s[6:7], vcc, s[6:7]
	v_add_u32_e32 v163, -6, v161
	v_max3_f32 v162, v162, v66, v67
	v_cndmask_b32_e64 v79, v79, v182, s[6:7]
	v_cmp_gt_u32_e64 s[6:7], s53, v163
	v_cmp_gt_i32_e64 s[8:9], v163, v133
	v_max3_f32 v162, v162, v68, v69
	s_or_b64 s[6:7], s[6:7], s[8:9]
	v_max3_f32 v162, v162, v70, v71
	v_mul_f32_e32 v80, 0x3e38aa3b, v80
	s_and_b64 s[6:7], vcc, s[6:7]
	v_add_u32_e32 v161, -5, v161
	v_max3_f32 v162, v162, v72, v73
	v_cndmask_b32_e64 v80, v80, v182, s[6:7]
	v_cmp_gt_u32_e64 s[6:7], s53, v161
	v_cmp_gt_i32_e64 s[8:9], v161, v133
	v_max3_f32 v162, v162, v74, v75
	s_or_b64 s[6:7], s[6:7], s[8:9]
	v_max3_f32 v162, v162, v76, v77
	v_mul_f32_e32 v81, 0x3e38aa3b, v81
	s_and_b64 vcc, vcc, s[6:7]
	v_max3_f32 v162, v162, v78, v79
	v_cndmask_b32_e32 v81, v81, v182, vcc
	v_max3_f32 v161, v162, v80, v81

; DEVI f32x16 mfma32(bf16x8 a, bf16x8 b, f32x16 c) { return __builtin_amdgcn_mfma_f32_32x32x16_bf16(a, b, c, 0, 0, 0); }
; template <bool SBK>
; __device__ __forceinline__ void attn_item(KP p, int layer, int b, int hh, int qt, char* smem, int tix) {
;     ...
;         float ps = 0.f;
; #pragma unroll
;         for (int kb2 = 0; kb2 < 2; ++kb2)
; #pragma unroll
;           for (int r = 0; r < 16; ++r) { float e = __builtin_amdgcn_exp2f(s[kb2][r] - m_run); s[kb2][r] = e; ps += e; }
;         l_run += ps;
;     ...
; #pragma unroll
;       for (int kb2 = 0; kb2 < 2; ++kb2)
; #pragma unroll
;         for (int s2 = 0; s2 < 2; ++s2) {
;           float tmp[8];
; #pragma unroll
;           for (int e = 0; e < 8; ++e) tmp[e] = s[kb2][8 * s2 + e];
;           pf[kb2][s2] = pack8(tmp);
;         }
;       asm volatile("s_nop 4" ::: "memory");
;       __builtin_amdgcn_s_setprio(1);
; #pragma unroll
;       for (int d = 0; d < NDV; ++d) {
;         const int vrow = (SBK ? c * 64 : 0) + d * 32 + l32;
; #pragma unroll
;         for (int kb2 = 0; kb2 < 2; ++kb2)
; #pragma unroll
;           for (int s2 = 0; s2 < 2; ++s2) {
;             const u16* vp = vb + vrow * VST + kb2 * 32 + 16 * s2 + 4 * hf;
;             bf16x4 lo = *(const bf16x4*)vp, hi = *(const bf16x4*)(vp + 8);
;             bf16x8 a = __builtin_shufflevector(lo, hi, 0, 1, 2, 3, 4, 5, 6, 7);
;             O[d] = mfma32(a, pf[kb2][s2], O[d]);
;           }
;       }
.LBB0_392:
	v_sub_f32_e32 v82, v82, v155
	v_exp_f32_e32 v82, v82
	v_sub_f32_e32 v83, v83, v155
	v_exp_f32_e32 v83, v83
	v_sub_f32_e32 v84, v84, v155
	v_exp_f32_e32 v84, v84
	v_sub_f32_e32 v85, v85, v155
	v_exp_f32_e32 v85, v85
	v_sub_f32_e32 v86, v86, v155
	v_add_f32_e32 v161, 0, v82
	v_exp_f32_e32 v86, v86
	v_sub_f32_e32 v87, v87, v155
	v_sub_f32_e32 v66, v66, v155
	v_add_f32_e32 v161, v83, v161
	v_exp_f32_e32 v87, v87
	v_sub_f32_e32 v88, v88, v155
	v_exp_f32_e32 v162, v66
	v_sub_f32_e32 v66, v67, v155
	v_add_f32_e32 v161, v84, v161
	v_exp_f32_e32 v88, v88
	v_sub_f32_e32 v89, v89, v155
	v_exp_f32_e32 v163, v66
	v_sub_f32_e32 v66, v68, v155
	v_add_f32_e32 v161, v85, v161
	v_exp_f32_e32 v89, v89
	v_sub_f32_e32 v90, v90, v155
	v_exp_f32_e32 v164, v66
	v_sub_f32_e32 v66, v69, v155
	v_add_f32_e32 v161, v86, v161
	v_exp_f32_e32 v90, v90
	v_sub_f32_e32 v91, v91, v155
	v_exp_f32_e32 v165, v66
	v_sub_f32_e32 v66, v70, v155
	v_add_f32_e32 v161, v87, v161
	v_exp_f32_e32 v91, v91
	v_sub_f32_e32 v92, v92, v155
	v_exp_f32_e32 v166, v66
	v_sub_f32_e32 v66, v71, v155
	v_add_f32_e32 v161, v88, v161
	v_exp_f32_e32 v92, v92
	v_sub_f32_e32 v93, v93, v155
	v_exp_f32_e32 v167, v66
	v_sub_f32_e32 v66, v72, v155
	v_add_f32_e32 v161, v89, v161
	v_exp_f32_e32 v93, v93
	v_sub_f32_e32 v94, v94, v155
	v_exp_f32_e32 v183, v66
	v_sub_f32_e32 v66, v73, v155
	v_add_f32_e32 v161, v90, v161
	v_exp_f32_e32 v94, v94
	v_sub_f32_e32 v95, v95, v155
	v_exp_f32_e32 v184, v66
	v_sub_f32_e32 v66, v74, v155
	v_add_f32_e32 v161, v91, v161
	v_exp_f32_e32 v95, v95
	v_sub_f32_e32 v96, v96, v155
	v_exp_f32_e32 v185, v66
	v_sub_f32_e32 v66, v75, v155
	v_add_f32_e32 v161, v92, v161
	v_exp_f32_e32 v96, v96
	v_sub_f32_e32 v97, v97, v155
	v_exp_f32_e32 v186, v66
	v_sub_f32_e32 v66, v76, v155
	v_add_f32_e32 v161, v93, v161
	v_exp_f32_e32 v97, v97
	v_exp_f32_e32 v187, v66
	v_sub_f32_e32 v66, v77, v155
	v_add_f32_e32 v161, v94, v161
	v_exp_f32_e32 v188, v66
	v_sub_f32_e32 v66, v78, v155
	v_add_f32_e32 v161, v95, v161
	v_exp_f32_e32 v189, v66
	v_sub_f32_e32 v66, v79, v155
	v_add_f32_e32 v161, v96, v161
	v_exp_f32_e32 v190, v66
	v_sub_f32_e32 v66, v80, v155
	v_add_f32_e32 v161, v97, v161
	v_exp_f32_e32 v191, v66
	v_sub_f32_e32 v66, v81, v155
	v_exp_f32_e32 v192, v66
	v_cvt_pk_bf16_f32 v66, v82, v83
	v_add_f32_e32 v82, v162, v161
	v_add_f32_e32 v82, v163, v82
	v_add_f32_e32 v82, v164, v82
	v_add_f32_e32 v82, v165, v82
	v_add_f32_e32 v82, v166, v82
	v_add_f32_e32 v82, v167, v82
	v_add_f32_e32 v82, v183, v82
	v_add_f32_e32 v82, v184, v82
	v_add_f32_e32 v82, v185, v82
	v_add_f32_e32 v82, v186, v82
	v_add_f32_e32 v82, v187, v82
	v_add_f32_e32 v82, v188, v82
	v_add_f32_e32 v82, v189, v82
	s_nop 4
	v_add_f32_e32 v82, v190, v82
	v_add_f32_e32 v82, v191, v82
	v_cvt_pk_bf16_f32 v67, v84, v85
	v_cvt_pk_bf16_f32 v68, v86, v87
	v_cvt_pk_bf16_f32 v69, v88, v89
	v_cvt_pk_bf16_f32 v70, v90, v91
	v_cvt_pk_bf16_f32 v71, v92, v93
	v_cvt_pk_bf16_f32 v72, v94, v95
	v_cvt_pk_bf16_f32 v73, v96, v97
	v_cvt_pk_bf16_f32 v74, v162, v163
	v_cvt_pk_bf16_f32 v75, v164, v165
	v_cvt_pk_bf16_f32 v76, v166, v167
	v_cvt_pk_bf16_f32 v77, v183, v184
	v_cvt_pk_bf16_f32 v78, v185, v186
	v_cvt_pk_bf16_f32 v79, v187, v188
	v_cvt_pk_bf16_f32 v80, v189, v190
	v_cvt_pk_bf16_f32 v81, v191, v192
	v_add_f32_e32 v86, v192, v82
	s_setprio 1
	v_add_u32_e32 v243, 0xb800, v242
	s_waitcnt lgkmcnt(0)
	ds_read2_b64 v[82:85], v243 offset0:96 offset1:98
	ds_read2_b64 v[90:93], v243 offset0:100 offset1:102
	ds_read2_b64 v[94:97], v243 offset0:104 offset1:106
	ds_read2_b64 v[162:165], v243 offset0:108 offset1:110
	v_add_f32_e32 v156, v156, v86
	v_mfma_f32_32x32x16_bf16 v[50:65], v[194:197], v[66:69], v[50:65]
	v_mfma_f32_32x32x16_bf16 v[34:49], v[210:213], v[66:69], v[34:49]
	v_mfma_f32_32x32x16_bf16 v[18:33], v[226:229], v[66:69], v[18:33]
	v_mfma_f32_32x32x16_bf16 v[50:65], v[198:201], v[70:73], v[50:65]
	v_mfma_f32_32x32x16_bf16 v[34:49], v[214:217], v[70:73], v[34:49]
	v_mfma_f32_32x32x16_bf16 v[18:33], v[230:233], v[70:73], v[18:33]
	v_mfma_f32_32x32x16_bf16 v[50:65], v[202:205], v[74:77], v[50:65]
	v_mfma_f32_32x32x16_bf16 v[34:49], v[218:221], v[74:77], v[34:49]
	v_mfma_f32_32x32x16_bf16 v[18:33], v[234:237], v[74:77], v[18:33]
	v_mfma_f32_32x32x16_bf16 v[50:65], v[206:209], v[78:81], v[50:65]
	v_mfma_f32_32x32x16_bf16 v[34:49], v[222:225], v[78:81], v[34:49]
	v_mfma_f32_32x32x16_bf16 v[18:33], v[238:241], v[78:81], v[18:33]
	s_waitcnt lgkmcnt(0)
	v_mfma_f32_32x32x16_bf16 v[2:17], v[82:85], v[66:69], v[2:17]
	v_mfma_f32_32x32x16_bf16 v[2:17], v[90:93], v[70:73], v[2:17]
	v_mfma_f32_32x32x16_bf16 v[2:17], v[94:97], v[74:77], v[2:17]
	v_mfma_f32_32x32x16_bf16 v[2:17], v[162:165], v[78:81], v[2:17]
	s_setprio 0
